# xcd barrier: XCD leader bumps the per-XCD generation word before its own L1 invalidate
# speedup vs baseline: 1.0092x; 1.0092x over previous
; __device__ __forceinline__ unsigned xb_add(unsigned* p, unsigned v) { return __hip_atomic_fetch_add(p, v, __ATOMIC_RELAXED, __HIP_MEMORY_SCOPE_AGENT); }
; __device__ __forceinline__ void xcd_barrier(unsigned* bar, volatile LAS unsigned* st, bool tid0, unsigned G) {
;     ...
;             __builtin_amdgcn_fence(__ATOMIC_ACQUIRE, "agent");
;             xb_add(&bar[XB_XGEN(x)], 1u);
;             asm volatile("s_waitcnt vmcnt(0)" ::: "memory");
.LBB0_1016:
	s_or_b64 exec, exec, s[8:9]
	s_mov_b64 s[2:3], exec
	v_mbcnt_lo_u32_b32 v0, s2, 0
	v_mbcnt_hi_u32_b32 v0, s3, v0
	v_cmp_eq_u32_e32 vcc, 0, v0
	s_waitcnt vmcnt(0)
	s_and_saveexec_b64 s[8:9], vcc
	s_cbranch_execz .LBB0_1018
	s_bcnt1_i32_b64 s2, s[2:3]
	v_mov_b32_e32 v0, s2
	global_atomic_add v241, v0, s[6:7] offset:1024
.LBB0_1018:
	s_or_b64 exec, exec, s[8:9]
	buffer_inv sc1
	s_waitcnt vmcnt(0)
